# write-through (sc1) also for the final f32 output stores of the second out-proj epilogue (layer 1)
# baseline (speedup 1.0000x reference)
; DI void unit_O(const Params& p, char* lds, int l, int tile, int glu_tiles, int tile_b) {
;     ...
; #pragma unroll 1
;             for (int i = 0; i < 8; ++i) {
;                 const int pc = (wid * 8 + i + (xrot >> 1)) & 63, kt = pc >> 1, sub = pc & 1;
;                 __builtin_amdgcn_global_load_lds((const unsigned*)(xbres + ((size_t)kt * 128 + half * 32) * 32 + sub * 512 + lane * 8), (unsigned*)(XR + pc * 1024 + lane * 16), 16, 0, 0);
;             }
;         }
;     };
;     issue_x(0);
;     {
;         const float* gsrc = (tid < 256) ? (p.ln_g + l * 1024 + tid * 4) : (p.ln_b + l * 1024 + (tid - 256) * 4);
;         *(f32x4*)(GB + tid * 4) = *(const f32x4*)gsrc;
;     }
;     float* xo = (l == 0) ? WS_PTR(float, OFF_X1) : p.out;
;     bf16_t* xbo = WS_PTR(bf16_t, OFF_XB1);
; #pragma unroll
;     for (int half = 0; half < 2; ++half) {
;         if (half == 0) wait_vm<0>();
;         else wait_vm<8>();
;         __syncthreads();
;         float s2[2], ss2[2];
; #pragma unroll
;         for (int mh = 0; mh < 2; ++mh) {
;             const int mt = half * 2 + mh, rl = mh * 16 + l15;
;             float s = 0.f, ss = 0.f;
; #pragma unroll
;             for (int nt = 0; nt < 8; ++nt) {
;                 f32x4 xr;
;                 if (l == 0) {
;                     const int chunk = wid * 32 + nt * 4 + quad;
;                     xr = *(const f32x4*)(XR + rl * 4096 + ((chunk ^ l15) << 4));
;                 } else {
;                     const u32x2 hb = *(const u32x2*)(XR + ((wid * 4 + (nt >> 1)) * 32 + rl) * 64 + (nt & 1) * 32 + quad * 8);
;                     xr = (f32x4){bf2f(hb[0] & 0xffffu), bf2f(hb[0] >> 16), bf2f(hb[1] & 0xffffu), bf2f(hb[1] >> 16)};
;                 }
; #pragma unroll
;                 for (int i = 0; i < 4; ++i) { const float v = acc[mt][nt][i] + DN_ALPHA * xr[i]; acc[mt][nt][i] = v; s += v; ss += v * v; }
;             }
;             s2[mh] = s; ss2[mh] = ss;
;         }
; #pragma unroll
;         for (int mh = 0; mh < 2; ++mh) { s2[mh] += __shfl_xor(s2[mh], 16); ss2[mh] += __shfl_xor(ss2[mh], 16); }
; #pragma unroll
;         for (int mh = 0; mh < 2; ++mh) { s2[mh] += __shfl_xor(s2[mh], 32); ss2[mh] += __shfl_xor(ss2[mh], 32); }
;         if (quad == 0) {
; #pragma unroll
;             for (int mh = 0; mh < 2; ++mh) *(f32x2*)&red[((mh * 16 + l15) * 8 + wid) * 2] = (f32x2){s2[mh], ss2[mh]};
;         }
;         __syncthreads();
.Le2_l1:
	s_lshr_b32 s40, s48, 1
	s_lshl_b32 s40, s40, 18
	s_and_b32 s94, s48, 1
	s_lshl_b32 s94, s94, 12
	s_add_u32 s40, s40, s94
	s_lshl_b32 s91, s90, 12
	s_lshl_b32 s94, s90, 15
	s_add_u32 s96, s56, s40
	s_addc_u32 s97, s57, 0
	s_add_u32 s96, s96, s94
	s_addc_u32 s97, s97, 0
	v_lshlrev_b32_e32 v208, 4, v141
	v_lshlrev_b32_e32 v133, 12, v140
	v_lshl_add_u32 v133, v138, 6, v133
	v_lshl_add_u32 v133, v139, 3, v133
	v_lshlrev_b32_e32 v137, 12, v138
	v_lshl_add_u32 v137, v140, 9, v137
	v_lshl_add_u32 v137, v139, 4, v137
	s_lshl_b32 s40, s48, 18
	s_add_u32 s78, s16, s40
	s_addc_u32 s79, s17, 0
	s_add_u32 s92, s96, 0x0
	s_addc_u32 s93, s97, 0
	s_add_u32 s40, s91, 0x0
	s_mov_b32 m0, s40
	s_nop 0
	global_load_lds_dwordx4 v208, s[92:93]
	s_add_u32 s92, s92, 0x2000
	s_addc_u32 s93, s93, 0
	s_add_u32 m0, m0, 0x400
	s_nop 0
	global_load_lds_dwordx4 v208, s[92:93]
	s_add_u32 s92, s92, 0x2000
	s_addc_u32 s93, s93, 0
	s_add_u32 m0, m0, 0x400
	s_nop 0
	global_load_lds_dwordx4 v208, s[92:93]
	s_add_u32 s92, s92, 0x2000
	s_addc_u32 s93, s93, 0
	s_add_u32 m0, m0, 0x400
	s_nop 0
	global_load_lds_dwordx4 v208, s[92:93]
	s_add_u32 s92, s96, 0x400
	s_addc_u32 s93, s97, 0
	s_add_u32 s40, s91, 0x8000
	s_mov_b32 m0, s40
	s_nop 0
	global_load_lds_dwordx4 v208, s[92:93]
	s_add_u32 s92, s92, 0x2000
	s_addc_u32 s93, s93, 0
	s_add_u32 m0, m0, 0x400
	s_nop 0
	global_load_lds_dwordx4 v208, s[92:93]
	s_add_u32 s92, s92, 0x2000
	s_addc_u32 s93, s93, 0
	s_add_u32 m0, m0, 0x400
	s_nop 0
	global_load_lds_dwordx4 v208, s[92:93]
	s_add_u32 s92, s92, 0x2000
	s_addc_u32 s93, s93, 0
	s_add_u32 m0, m0, 0x400
	s_nop 0
	global_load_lds_dwordx4 v208, s[92:93]
	s_waitcnt vmcnt(8)
	ds_write_b128 v143, v[176:179]
	s_waitcnt vmcnt(4) lgkmcnt(0)
	s_barrier
	ds_read_b64 v[180:181], v133 offset:0
	ds_read_b64 v[182:183], v133 offset:32
	ds_read_b64 v[184:185], v133 offset:1024
	ds_read_b64 v[186:187], v133 offset:1056
	ds_read_b64 v[188:189], v133 offset:2048
	ds_read_b64 v[190:191], v133 offset:2080
	ds_read_b64 v[192:193], v133 offset:3072
	ds_read_b64 v[194:195], v133 offset:3104
	s_waitcnt lgkmcnt(7)
	v_lshlrev_b32_e32 v144, 16, v180
	v_and_b32_e32 v145, 0xffff0000, v180
	v_lshlrev_b32_e32 v146, 16, v181
	v_and_b32_e32 v147, 0xffff0000, v181
	v_fmac_f32_e32 v98, s58, v144
	v_fmac_f32_e32 v99, s58, v145
	v_fmac_f32_e32 v100, s58, v146
	v_fmac_f32_e32 v101, s58, v147
	v_mov_b32_e32 v196, v98
	v_mul_f32_e32 v197, v98, v98
	v_mov_b32_e32 v130, v99
	v_mul_f32_e32 v142, v99, v99
	v_add_f32_e32 v196, v196, v100
	v_fmac_f32_e32 v197, v100, v100
	v_add_f32_e32 v130, v130, v101
	v_fmac_f32_e32 v142, v101, v101
	s_waitcnt lgkmcnt(6)
	v_lshlrev_b32_e32 v148, 16, v182
	v_and_b32_e32 v149, 0xffff0000, v182
	v_lshlrev_b32_e32 v150, 16, v183
	v_and_b32_e32 v151, 0xffff0000, v183
	v_fmac_f32_e32 v94, s58, v148
	v_fmac_f32_e32 v95, s58, v149
	v_fmac_f32_e32 v96, s58, v150
	v_fmac_f32_e32 v97, s58, v151
	v_add_f32_e32 v196, v196, v94
	v_fmac_f32_e32 v197, v94, v94
	v_add_f32_e32 v130, v130, v95
	v_fmac_f32_e32 v142, v95, v95
	v_add_f32_e32 v196, v196, v96
	v_fmac_f32_e32 v197, v96, v96
	v_add_f32_e32 v130, v130, v97
	v_fmac_f32_e32 v142, v97, v97
	s_waitcnt lgkmcnt(5)
	v_lshlrev_b32_e32 v152, 16, v184
	v_and_b32_e32 v153, 0xffff0000, v184
	v_lshlrev_b32_e32 v154, 16, v185
	v_and_b32_e32 v155, 0xffff0000, v185
	v_fmac_f32_e32 v90, s58, v152
	v_fmac_f32_e32 v91, s58, v153
	v_fmac_f32_e32 v92, s58, v154
	v_fmac_f32_e32 v93, s58, v155
	v_add_f32_e32 v196, v196, v90
	v_fmac_f32_e32 v197, v90, v90
	v_add_f32_e32 v130, v130, v91
	v_fmac_f32_e32 v142, v91, v91
	v_add_f32_e32 v196, v196, v92
	v_fmac_f32_e32 v197, v92, v92
	v_add_f32_e32 v130, v130, v93
	v_fmac_f32_e32 v142, v93, v93
	s_waitcnt lgkmcnt(4)
	v_lshlrev_b32_e32 v156, 16, v186
	v_and_b32_e32 v157, 0xffff0000, v186
	v_lshlrev_b32_e32 v158, 16, v187
	v_and_b32_e32 v159, 0xffff0000, v187
	v_fmac_f32_e32 v86, s58, v156
	v_fmac_f32_e32 v87, s58, v157
	v_fmac_f32_e32 v88, s58, v158
	v_fmac_f32_e32 v89, s58, v159
	v_add_f32_e32 v196, v196, v86
	v_fmac_f32_e32 v197, v86, v86
	v_add_f32_e32 v130, v130, v87
	v_fmac_f32_e32 v142, v87, v87
	v_add_f32_e32 v196, v196, v88
	v_fmac_f32_e32 v197, v88, v88
	v_add_f32_e32 v130, v130, v89
	v_fmac_f32_e32 v142, v89, v89
	s_waitcnt lgkmcnt(3)
	v_lshlrev_b32_e32 v160, 16, v188
	v_and_b32_e32 v161, 0xffff0000, v188
	v_lshlrev_b32_e32 v162, 16, v189
	v_and_b32_e32 v163, 0xffff0000, v189
	v_fmac_f32_e32 v82, s58, v160
	v_fmac_f32_e32 v83, s58, v161
	v_fmac_f32_e32 v84, s58, v162
	v_fmac_f32_e32 v85, s58, v163
	v_add_f32_e32 v196, v196, v82
	v_fmac_f32_e32 v197, v82, v82
	v_add_f32_e32 v130, v130, v83
	v_fmac_f32_e32 v142, v83, v83
	v_add_f32_e32 v196, v196, v84
	v_fmac_f32_e32 v197, v84, v84
	v_add_f32_e32 v130, v130, v85
	v_fmac_f32_e32 v142, v85, v85
	s_waitcnt lgkmcnt(2)
	v_lshlrev_b32_e32 v164, 16, v190
	v_and_b32_e32 v165, 0xffff0000, v190
	v_lshlrev_b32_e32 v166, 16, v191
	v_and_b32_e32 v167, 0xffff0000, v191
	v_fmac_f32_e32 v78, s58, v164
	v_fmac_f32_e32 v79, s58, v165
	v_fmac_f32_e32 v80, s58, v166
	v_fmac_f32_e32 v81, s58, v167
	v_add_f32_e32 v196, v196, v78
	v_fmac_f32_e32 v197, v78, v78
	v_add_f32_e32 v130, v130, v79
	v_fmac_f32_e32 v142, v79, v79
	v_add_f32_e32 v196, v196, v80
	v_fmac_f32_e32 v197, v80, v80
	v_add_f32_e32 v130, v130, v81
	v_fmac_f32_e32 v142, v81, v81
	s_waitcnt lgkmcnt(1)
	v_lshlrev_b32_e32 v168, 16, v192
	v_and_b32_e32 v169, 0xffff0000, v192
	v_lshlrev_b32_e32 v170, 16, v193
	v_and_b32_e32 v171, 0xffff0000, v193
	v_fmac_f32_e32 v74, s58, v168
	v_fmac_f32_e32 v75, s58, v169
	v_fmac_f32_e32 v76, s58, v170
	v_fmac_f32_e32 v77, s58, v171
	v_add_f32_e32 v196, v196, v74
	v_fmac_f32_e32 v197, v74, v74
	v_add_f32_e32 v130, v130, v75
	v_fmac_f32_e32 v142, v75, v75
	v_add_f32_e32 v196, v196, v76
	v_fmac_f32_e32 v197, v76, v76
	v_add_f32_e32 v130, v130, v77
	v_fmac_f32_e32 v142, v77, v77
	s_waitcnt lgkmcnt(0)
	v_lshlrev_b32_e32 v172, 16, v194
	v_and_b32_e32 v173, 0xffff0000, v194
	v_lshlrev_b32_e32 v174, 16, v195
	v_and_b32_e32 v175, 0xffff0000, v195
	v_fmac_f32_e32 v70, s58, v172
	v_fmac_f32_e32 v71, s58, v173
	v_fmac_f32_e32 v72, s58, v174
	v_fmac_f32_e32 v73, s58, v175
	v_add_f32_e32 v196, v196, v70
	v_fmac_f32_e32 v197, v70, v70
	v_add_f32_e32 v130, v130, v71
	v_fmac_f32_e32 v142, v71, v71
	v_add_f32_e32 v196, v196, v72
	v_fmac_f32_e32 v197, v72, v72
	v_add_f32_e32 v130, v130, v73
	v_fmac_f32_e32 v142, v73, v73
	v_add_f32_e32 v196, v196, v130
	v_add_f32_e32 v197, v197, v142
	v_mov_b32_e32 v198, v196
	v_mov_b32_e32 v199, v197
	s_nop 1
	v_permlane16_swap_b32 v198, v196
	v_permlane16_swap_b32 v199, v197
	v_add_f32_e32 v196, v196, v198
	v_add_f32_e32 v197, v197, v199
	v_mov_b32_e32 v198, v196
	v_mov_b32_e32 v199, v197
	s_nop 1
	v_permlane32_swap_b32 v198, v196
	v_permlane32_swap_b32 v199, v197
	v_add_f32_e32 v196, v196, v198
	v_add_f32_e32 v197, v197, v199
	s_mov_b64 exec, 0xffff
	ds_write_b64 v134, v[196:197]
	s_mov_b64 exec, -1
	s_waitcnt lgkmcnt(0)
	s_barrier
; DI unsigned pk2(float lo, float hi) { const f32x2 v = {lo, hi}; const bf16x2_t b = __builtin_convertvector(v, bf16x2_t); return __builtin_bit_cast(unsigned, b); }
; DI size_t xb_off(int tok, int col) { return ((size_t)(((tok >> 7) * 32 + (col >> 5)) * 128 + (tok & 127))) * 32 + (col & 31); }
; DI void unit_O(const Params& p, char* lds, int l, int tile, int glu_tiles, int tile_b) {
;     ...
;         if (half == 0) issue_x(1);
; #pragma unroll
;         for (int mh = 0; mh < 2; ++mh) {
;             const int mt = half * 2 + mh, rl = mh * 16 + l15, row = mt * 16 + l15;
;             float s = 0.f, ss = 0.f;
; #pragma unroll
;             for (int w = 0; w < 4; ++w) { const f32x4 v = *(const f32x4*)&red[rl * 16 + 4 * w]; s += v[0] + v[2]; ss += v[1] + v[3]; }
;             const float mu = s * (1.f / 1024.f);
;             const float var = ss * (1.f / 1024.f) - mu * mu;
;             const float rs = rsqrtf(var + LN_EPS);
;             float* orow = xo + (r0 + row) * 1024 + wid * 128 + quad * 4;
;             bf16_t* brow = xbo + xb_off((int)r0 + row, wid * 128) + quad * 4;
;             const float* gp = GB + wid * 128 + quad * 4;
; #pragma unroll
;             for (int nt = 0; nt < 8; ++nt) {
;                 const f32x4 g = *(const f32x4*)(gp + nt * 16), bb = *(const f32x4*)(gp + 1024 + nt * 16);
;                 f32x4 o;
; #pragma unroll
;                 for (int i = 0; i < 4; ++i) o[i] = (acc[mt][nt][i] - mu) * rs * g[i] + bb[i];
;                 if (l == 0) *(u32x2*)(brow + (nt >> 1) * 4096 + (nt & 1) * 16) = (u32x2){pk2(o[0], o[1]), pk2(o[2], o[3])};
;                 else *(f32x4*)(orow + nt * 16) = o;
;             }
	s_add_u32 s92, s96, 0x800
	s_addc_u32 s93, s97, 0
	s_add_u32 s40, s91, 0x0
	s_mov_b32 m0, s40
	s_nop 0
	global_load_lds_dwordx4 v208, s[92:93]
	s_add_u32 s92, s92, 0x2000
	s_addc_u32 s93, s93, 0
	s_add_u32 m0, m0, 0x400
	s_nop 0
	global_load_lds_dwordx4 v208, s[92:93]
	s_add_u32 s92, s92, 0x2000
	s_addc_u32 s93, s93, 0
	s_add_u32 m0, m0, 0x400
	s_nop 0
	global_load_lds_dwordx4 v208, s[92:93]
	s_add_u32 s92, s92, 0x2000
	s_addc_u32 s93, s93, 0
	s_add_u32 m0, m0, 0x400
	s_nop 0
	global_load_lds_dwordx4 v208, s[92:93]
	ds_read_b128 v[160:163], v135 offset:0
	ds_read_b128 v[164:167], v135 offset:16
	ds_read_b128 v[168:171], v135 offset:32
	ds_read_b128 v[172:175], v135 offset:48
	s_waitcnt lgkmcnt(0)
	v_add_f32_e32 v160, v160, v162
	v_add_f32_e32 v161, v161, v163
	v_add_f32_e32 v164, v164, v166
	v_add_f32_e32 v165, v165, v167
	v_add_f32_e32 v168, v168, v170
	v_add_f32_e32 v169, v169, v171
	v_add_f32_e32 v172, v172, v174
	v_add_f32_e32 v173, v173, v175
	v_add_f32_e32 v160, v160, v164
	v_add_f32_e32 v161, v161, v165
	v_add_f32_e32 v168, v168, v172
	v_add_f32_e32 v169, v169, v173
	v_add_f32_e32 v160, v160, v168
	v_add_f32_e32 v161, v161, v169
	v_mul_f32_e32 v192, 0x3a800000, v160
	v_mul_f32_e32 v193, 0x3a800000, v161
	v_fma_f32 v193, -v192, v192, v193
	v_add_f32_e32 v193, 0x3727c5ac, v193
	v_rsq_f32_e32 v193, v193
	s_nop 0
	s_add_u32 s94, s78, 0x0
	s_addc_u32 s95, s79, 0
	ds_read_b128 v[176:179], v136
	ds_read_b128 v[180:183], v136 offset:4096
	ds_read_b128 v[184:187], v136 offset:64
	ds_read_b128 v[188:191], v136 offset:4160
	s_waitcnt lgkmcnt(2)
	v_sub_f32_e32 v98, v98, v192
	v_mul_f32_e32 v98, v98, v193
	v_fma_f32 v98, v176, v98, v180
	v_sub_f32_e32 v99, v99, v192
	v_mul_f32_e32 v99, v99, v193
	v_fma_f32 v99, v177, v99, v181
	v_sub_f32_e32 v100, v100, v192
	v_mul_f32_e32 v100, v100, v193
	v_fma_f32 v100, v178, v100, v182
	v_sub_f32_e32 v101, v101, v192
	v_mul_f32_e32 v101, v101, v193
	v_fma_f32 v101, v179, v101, v183
	global_store_dwordx4 v137, v[98:101], s[94:95] sc1
	ds_read_b128 v[176:179], v136 offset:128
	ds_read_b128 v[180:183], v136 offset:4224
	s_waitcnt lgkmcnt(2)
	v_sub_f32_e32 v94, v94, v192
	v_mul_f32_e32 v94, v94, v193
	v_fma_f32 v94, v184, v94, v188
	v_sub_f32_e32 v95, v95, v192
	v_mul_f32_e32 v95, v95, v193
	v_fma_f32 v95, v185, v95, v189
	v_sub_f32_e32 v96, v96, v192
	v_mul_f32_e32 v96, v96, v193
	v_fma_f32 v96, v186, v96, v190
	v_sub_f32_e32 v97, v97, v192
	v_mul_f32_e32 v97, v97, v193
	v_fma_f32 v97, v187, v97, v191
	global_store_dwordx4 v137, v[94:97], s[94:95] offset:64 sc1
	ds_read_b128 v[184:187], v136 offset:192
	ds_read_b128 v[188:191], v136 offset:4288
	s_waitcnt lgkmcnt(2)
	v_sub_f32_e32 v90, v90, v192
	v_mul_f32_e32 v90, v90, v193
	v_fma_f32 v90, v176, v90, v180
	v_sub_f32_e32 v91, v91, v192
	v_mul_f32_e32 v91, v91, v193
	v_fma_f32 v91, v177, v91, v181
	v_sub_f32_e32 v92, v92, v192
	v_mul_f32_e32 v92, v92, v193
	v_fma_f32 v92, v178, v92, v182
	v_sub_f32_e32 v93, v93, v192
	v_mul_f32_e32 v93, v93, v193
	v_fma_f32 v93, v179, v93, v183
	global_store_dwordx4 v137, v[90:93], s[94:95] offset:128 sc1
	ds_read_b128 v[176:179], v136 offset:256
	ds_read_b128 v[180:183], v136 offset:4352
	s_waitcnt lgkmcnt(2)
	v_sub_f32_e32 v86, v86, v192
	v_mul_f32_e32 v86, v86, v193
	v_fma_f32 v86, v184, v86, v188
	v_sub_f32_e32 v87, v87, v192
	v_mul_f32_e32 v87, v87, v193
	v_fma_f32 v87, v185, v87, v189
	v_sub_f32_e32 v88, v88, v192
	v_mul_f32_e32 v88, v88, v193
	v_fma_f32 v88, v186, v88, v190
	v_sub_f32_e32 v89, v89, v192
	v_mul_f32_e32 v89, v89, v193
	v_fma_f32 v89, v187, v89, v191
	global_store_dwordx4 v137, v[86:89], s[94:95] offset:192 sc1
	ds_read_b128 v[184:187], v136 offset:320
	ds_read_b128 v[188:191], v136 offset:4416
	s_waitcnt lgkmcnt(2)
	v_sub_f32_e32 v82, v82, v192
	v_mul_f32_e32 v82, v82, v193
	v_fma_f32 v82, v176, v82, v180
	v_sub_f32_e32 v83, v83, v192
	v_mul_f32_e32 v83, v83, v193
	v_fma_f32 v83, v177, v83, v181
	v_sub_f32_e32 v84, v84, v192
	v_mul_f32_e32 v84, v84, v193
	v_fma_f32 v84, v178, v84, v182
	v_sub_f32_e32 v85, v85, v192
	v_mul_f32_e32 v85, v85, v193
	v_fma_f32 v85, v179, v85, v183
	global_store_dwordx4 v137, v[82:85], s[94:95] offset:256 sc1
	ds_read_b128 v[176:179], v136 offset:384
	ds_read_b128 v[180:183], v136 offset:4480
	s_waitcnt lgkmcnt(2)
	v_sub_f32_e32 v78, v78, v192
	v_mul_f32_e32 v78, v78, v193
	v_fma_f32 v78, v184, v78, v188
	v_sub_f32_e32 v79, v79, v192
	v_mul_f32_e32 v79, v79, v193
	v_fma_f32 v79, v185, v79, v189
	v_sub_f32_e32 v80, v80, v192
	v_mul_f32_e32 v80, v80, v193
	v_fma_f32 v80, v186, v80, v190
	v_sub_f32_e32 v81, v81, v192
	v_mul_f32_e32 v81, v81, v193
	v_fma_f32 v81, v187, v81, v191
	global_store_dwordx4 v137, v[78:81], s[94:95] offset:320 sc1
	ds_read_b128 v[184:187], v136 offset:448
	ds_read_b128 v[188:191], v136 offset:4544
	s_waitcnt lgkmcnt(2)
	v_sub_f32_e32 v74, v74, v192
	v_mul_f32_e32 v74, v74, v193
	v_fma_f32 v74, v176, v74, v180
	v_sub_f32_e32 v75, v75, v192
	v_mul_f32_e32 v75, v75, v193
	v_fma_f32 v75, v177, v75, v181
	v_sub_f32_e32 v76, v76, v192
	v_mul_f32_e32 v76, v76, v193
	v_fma_f32 v76, v178, v76, v182
	v_sub_f32_e32 v77, v77, v192
	v_mul_f32_e32 v77, v77, v193
	v_fma_f32 v77, v179, v77, v183
	global_store_dwordx4 v137, v[74:77], s[94:95] offset:384 sc1
	s_waitcnt lgkmcnt(0)
	v_sub_f32_e32 v70, v70, v192
	v_mul_f32_e32 v70, v70, v193
	v_fma_f32 v70, v184, v70, v188
	v_sub_f32_e32 v71, v71, v192
	v_mul_f32_e32 v71, v71, v193
	v_fma_f32 v71, v185, v71, v189
	v_sub_f32_e32 v72, v72, v192
	v_mul_f32_e32 v72, v72, v193
	v_fma_f32 v72, v186, v72, v190
	v_sub_f32_e32 v73, v73, v192
	v_mul_f32_e32 v73, v73, v193
	v_fma_f32 v73, v187, v73, v191
	global_store_dwordx4 v137, v[70:73], s[94:95] offset:448 sc1
	s_waitcnt vmcnt(12) lgkmcnt(0)
	s_barrier
; DI float bf2f(unsigned b) { return __uint_as_float(b << 16); }
; DI void unit_O(const Params& p, char* lds, int l, int tile, int glu_tiles, int tile_b) {
;     ...
;         float s2[2], ss2[2];
; #pragma unroll
;         for (int mh = 0; mh < 2; ++mh) {
;             const int mt = half * 2 + mh, rl = mh * 16 + l15;
;             float s = 0.f, ss = 0.f;
; #pragma unroll
;             for (int nt = 0; nt < 8; ++nt) {
;                 f32x4 xr;
;                 if (l == 0) {
;                     const int chunk = wid * 32 + nt * 4 + quad;
;                     xr = *(const f32x4*)(XR + rl * 4096 + ((chunk ^ l15) << 4));
;                 } else {
;                     const u32x2 hb = *(const u32x2*)(XR + ((wid * 4 + (nt >> 1)) * 32 + rl) * 64 + (nt & 1) * 32 + quad * 8);
;                     xr = (f32x4){bf2f(hb[0] & 0xffffu), bf2f(hb[0] >> 16), bf2f(hb[1] & 0xffffu), bf2f(hb[1] >> 16)};
;                 }
; #pragma unroll
;                 for (int i = 0; i < 4; ++i) { const float v = acc[mt][nt][i] + DN_ALPHA * xr[i]; acc[mt][nt][i] = v; s += v; ss += v * v; }
;             }
;             s2[mh] = s; ss2[mh] = ss;
;         }
; #pragma unroll
;         for (int mh = 0; mh < 2; ++mh) { s2[mh] += __shfl_xor(s2[mh], 16); ss2[mh] += __shfl_xor(ss2[mh], 16); }
; #pragma unroll
;         for (int mh = 0; mh < 2; ++mh) { s2[mh] += __shfl_xor(s2[mh], 32); ss2[mh] += __shfl_xor(ss2[mh], 32); }
;         if (quad == 0) {
; #pragma unroll
;             for (int mh = 0; mh < 2; ++mh) *(f32x2*)&red[((mh * 16 + l15) * 8 + wid) * 2] = (f32x2){s2[mh], ss2[mh]};
;         }
;         __syncthreads();
	ds_read_b64 v[180:181], v133 offset:32768
	ds_read_b64 v[182:183], v133 offset:32800
	ds_read_b64 v[184:185], v133 offset:33792
	ds_read_b64 v[186:187], v133 offset:33824
	ds_read_b64 v[188:189], v133 offset:34816
	ds_read_b64 v[190:191], v133 offset:34848
	ds_read_b64 v[192:193], v133 offset:35840
	ds_read_b64 v[194:195], v133 offset:35872
	s_waitcnt lgkmcnt(7)
	v_lshlrev_b32_e32 v144, 16, v180
	v_and_b32_e32 v145, 0xffff0000, v180
	v_lshlrev_b32_e32 v146, 16, v181
	v_and_b32_e32 v147, 0xffff0000, v181
	v_fmac_f32_e32 v126, s58, v144
	v_fmac_f32_e32 v127, s58, v145
	v_fmac_f32_e32 v128, s58, v146
	v_fmac_f32_e32 v129, s58, v147
	v_mov_b32_e32 v196, v126
	v_mul_f32_e32 v197, v126, v126
	v_mov_b32_e32 v130, v127
	v_mul_f32_e32 v142, v127, v127
	v_add_f32_e32 v196, v196, v128
	v_fmac_f32_e32 v197, v128, v128
	v_add_f32_e32 v130, v130, v129
	v_fmac_f32_e32 v142, v129, v129
	s_waitcnt lgkmcnt(6)
	v_lshlrev_b32_e32 v148, 16, v182
	v_and_b32_e32 v149, 0xffff0000, v182
	v_lshlrev_b32_e32 v150, 16, v183
	v_and_b32_e32 v151, 0xffff0000, v183
	v_fmac_f32_e32 v122, s58, v148
	v_fmac_f32_e32 v123, s58, v149
	v_fmac_f32_e32 v124, s58, v150
	v_fmac_f32_e32 v125, s58, v151
	v_add_f32_e32 v196, v196, v122
	v_fmac_f32_e32 v197, v122, v122
	v_add_f32_e32 v130, v130, v123
	v_fmac_f32_e32 v142, v123, v123
	v_add_f32_e32 v196, v196, v124
	v_fmac_f32_e32 v197, v124, v124
	v_add_f32_e32 v130, v130, v125
	v_fmac_f32_e32 v142, v125, v125
	s_waitcnt lgkmcnt(5)
	v_lshlrev_b32_e32 v152, 16, v184
	v_and_b32_e32 v153, 0xffff0000, v184
	v_lshlrev_b32_e32 v154, 16, v185
	v_and_b32_e32 v155, 0xffff0000, v185
	v_fmac_f32_e32 v118, s58, v152
	v_fmac_f32_e32 v119, s58, v153
	v_fmac_f32_e32 v120, s58, v154
	v_fmac_f32_e32 v121, s58, v155
	v_add_f32_e32 v196, v196, v118
	v_fmac_f32_e32 v197, v118, v118
	v_add_f32_e32 v130, v130, v119
	v_fmac_f32_e32 v142, v119, v119
	v_add_f32_e32 v196, v196, v120
	v_fmac_f32_e32 v197, v120, v120
	v_add_f32_e32 v130, v130, v121
	v_fmac_f32_e32 v142, v121, v121
	s_waitcnt lgkmcnt(4)
	v_lshlrev_b32_e32 v156, 16, v186
	v_and_b32_e32 v157, 0xffff0000, v186
	v_lshlrev_b32_e32 v158, 16, v187
	v_and_b32_e32 v159, 0xffff0000, v187
	v_fmac_f32_e32 v114, s58, v156
	v_fmac_f32_e32 v115, s58, v157
	v_fmac_f32_e32 v116, s58, v158
	v_fmac_f32_e32 v117, s58, v159
	v_add_f32_e32 v196, v196, v114
	v_fmac_f32_e32 v197, v114, v114
	v_add_f32_e32 v130, v130, v115
	v_fmac_f32_e32 v142, v115, v115
	v_add_f32_e32 v196, v196, v116
	v_fmac_f32_e32 v197, v116, v116
	v_add_f32_e32 v130, v130, v117
	v_fmac_f32_e32 v142, v117, v117
	s_waitcnt lgkmcnt(3)
	v_lshlrev_b32_e32 v160, 16, v188
	v_and_b32_e32 v161, 0xffff0000, v188
	v_lshlrev_b32_e32 v162, 16, v189
	v_and_b32_e32 v163, 0xffff0000, v189
	v_fmac_f32_e32 v110, s58, v160
	v_fmac_f32_e32 v111, s58, v161
	v_fmac_f32_e32 v112, s58, v162
	v_fmac_f32_e32 v113, s58, v163
	v_add_f32_e32 v196, v196, v110
	v_fmac_f32_e32 v197, v110, v110
	v_add_f32_e32 v130, v130, v111
	v_fmac_f32_e32 v142, v111, v111
	v_add_f32_e32 v196, v196, v112
	v_fmac_f32_e32 v197, v112, v112
	v_add_f32_e32 v130, v130, v113
	v_fmac_f32_e32 v142, v113, v113
	s_waitcnt lgkmcnt(2)
	v_lshlrev_b32_e32 v164, 16, v190
	v_and_b32_e32 v165, 0xffff0000, v190
	v_lshlrev_b32_e32 v166, 16, v191
	v_and_b32_e32 v167, 0xffff0000, v191
	v_fmac_f32_e32 v106, s58, v164
	v_fmac_f32_e32 v107, s58, v165
	v_fmac_f32_e32 v108, s58, v166
	v_fmac_f32_e32 v109, s58, v167
	v_add_f32_e32 v196, v196, v106
	v_fmac_f32_e32 v197, v106, v106
	v_add_f32_e32 v130, v130, v107
	v_fmac_f32_e32 v142, v107, v107
	v_add_f32_e32 v196, v196, v108
	v_fmac_f32_e32 v197, v108, v108
	v_add_f32_e32 v130, v130, v109
	v_fmac_f32_e32 v142, v109, v109
	s_waitcnt lgkmcnt(1)
	v_lshlrev_b32_e32 v168, 16, v192
	v_and_b32_e32 v169, 0xffff0000, v192
	v_lshlrev_b32_e32 v170, 16, v193
	v_and_b32_e32 v171, 0xffff0000, v193
	v_fmac_f32_e32 v102, s58, v168
	v_fmac_f32_e32 v103, s58, v169
	v_fmac_f32_e32 v104, s58, v170
	v_fmac_f32_e32 v105, s58, v171
	v_add_f32_e32 v196, v196, v102
	v_fmac_f32_e32 v197, v102, v102
	v_add_f32_e32 v130, v130, v103
	v_fmac_f32_e32 v142, v103, v103
	v_add_f32_e32 v196, v196, v104
	v_fmac_f32_e32 v197, v104, v104
	v_add_f32_e32 v130, v130, v105
	v_fmac_f32_e32 v142, v105, v105
	s_waitcnt lgkmcnt(0)
	v_lshlrev_b32_e32 v172, 16, v194
	v_and_b32_e32 v173, 0xffff0000, v194
	v_lshlrev_b32_e32 v174, 16, v195
	v_and_b32_e32 v175, 0xffff0000, v195
	v_fmac_f32_e32 v66, s58, v172
	v_fmac_f32_e32 v67, s58, v173
	v_fmac_f32_e32 v68, s58, v174
	v_fmac_f32_e32 v69, s58, v175
	v_add_f32_e32 v196, v196, v66
	v_fmac_f32_e32 v197, v66, v66
	v_add_f32_e32 v130, v130, v67
	v_fmac_f32_e32 v142, v67, v67
	v_add_f32_e32 v196, v196, v68
	v_fmac_f32_e32 v197, v68, v68
	v_add_f32_e32 v130, v130, v69
	v_fmac_f32_e32 v142, v69, v69
	v_add_f32_e32 v196, v196, v130
	v_add_f32_e32 v197, v197, v142
	v_mov_b32_e32 v198, v196
	v_mov_b32_e32 v199, v197
	s_nop 1
	v_permlane16_swap_b32 v198, v196
	v_permlane16_swap_b32 v199, v197
	v_add_f32_e32 v196, v196, v198
	v_add_f32_e32 v197, v197, v199
	v_mov_b32_e32 v198, v196
	v_mov_b32_e32 v199, v197
	s_nop 1
	v_permlane32_swap_b32 v198, v196
	v_permlane32_swap_b32 v199, v197
	v_add_f32_e32 v196, v196, v198
	v_add_f32_e32 v197, v197, v199
	s_mov_b64 exec, 0xffff
	ds_write_b64 v134, v[196:197]
	s_mov_b64 exec, -1
	s_waitcnt lgkmcnt(0)
	s_barrier
; DI unsigned pk2(float lo, float hi) { const f32x2 v = {lo, hi}; const bf16x2_t b = __builtin_convertvector(v, bf16x2_t); return __builtin_bit_cast(unsigned, b); }
; DI size_t xb_off(int tok, int col) { return ((size_t)(((tok >> 7) * 32 + (col >> 5)) * 128 + (tok & 127))) * 32 + (col & 31); }
; DI void unit_O(const Params& p, char* lds, int l, int tile, int glu_tiles, int tile_b) {
;     ...
;         if (half == 0) issue_x(1);
; #pragma unroll
;         for (int mh = 0; mh < 2; ++mh) {
;             const int mt = half * 2 + mh, rl = mh * 16 + l15, row = mt * 16 + l15;
;             float s = 0.f, ss = 0.f;
; #pragma unroll
;             for (int w = 0; w < 4; ++w) { const f32x4 v = *(const f32x4*)&red[rl * 16 + 4 * w]; s += v[0] + v[2]; ss += v[1] + v[3]; }
;             const float mu = s * (1.f / 1024.f);
;             const float var = ss * (1.f / 1024.f) - mu * mu;
;             const float rs = rsqrtf(var + LN_EPS);
;             float* orow = xo + (r0 + row) * 1024 + wid * 128 + quad * 4;
;             bf16_t* brow = xbo + xb_off((int)r0 + row, wid * 128) + quad * 4;
;             const float* gp = GB + wid * 128 + quad * 4;
; #pragma unroll
;             for (int nt = 0; nt < 8; ++nt) {
;                 const f32x4 g = *(const f32x4*)(gp + nt * 16), bb = *(const f32x4*)(gp + 1024 + nt * 16);
;                 f32x4 o;
; #pragma unroll
;                 for (int i = 0; i < 4; ++i) o[i] = (acc[mt][nt][i] - mu) * rs * g[i] + bb[i];
;                 if (l == 0) *(u32x2*)(brow + (nt >> 1) * 4096 + (nt & 1) * 16) = (u32x2){pk2(o[0], o[1]), pk2(o[2], o[3])};
;                 else *(f32x4*)(orow + nt * 16) = o;
;             }
	s_add_u32 s92, s96, 0xc00
	s_addc_u32 s93, s97, 0
	s_add_u32 s40, s91, 0x8000
	s_mov_b32 m0, s40
	s_nop 0
	global_load_lds_dwordx4 v208, s[92:93]
	s_add_u32 s92, s92, 0x2000
	s_addc_u32 s93, s93, 0
	s_add_u32 m0, m0, 0x400
	s_nop 0
	global_load_lds_dwordx4 v208, s[92:93]
	s_add_u32 s92, s92, 0x2000
	s_addc_u32 s93, s93, 0
	s_add_u32 m0, m0, 0x400
	s_nop 0
	global_load_lds_dwordx4 v208, s[92:93]
	s_add_u32 s92, s92, 0x2000
	s_addc_u32 s93, s93, 0
	s_add_u32 m0, m0, 0x400
	s_nop 0
	global_load_lds_dwordx4 v208, s[92:93]
	ds_read_b128 v[160:163], v135 offset:0
	ds_read_b128 v[164:167], v135 offset:16
	ds_read_b128 v[168:171], v135 offset:32
	ds_read_b128 v[172:175], v135 offset:48
	s_waitcnt lgkmcnt(0)
	v_add_f32_e32 v160, v160, v162
	v_add_f32_e32 v161, v161, v163
	v_add_f32_e32 v164, v164, v166
	v_add_f32_e32 v165, v165, v167
	v_add_f32_e32 v168, v168, v170
	v_add_f32_e32 v169, v169, v171
	v_add_f32_e32 v172, v172, v174
	v_add_f32_e32 v173, v173, v175
	v_add_f32_e32 v160, v160, v164
	v_add_f32_e32 v161, v161, v165
	v_add_f32_e32 v168, v168, v172
	v_add_f32_e32 v169, v169, v173
	v_add_f32_e32 v160, v160, v168
	v_add_f32_e32 v161, v161, v169
	v_mul_f32_e32 v192, 0x3a800000, v160
	v_mul_f32_e32 v193, 0x3a800000, v161
	v_fma_f32 v193, -v192, v192, v193
	v_add_f32_e32 v193, 0x3727c5ac, v193
	v_rsq_f32_e32 v193, v193
	s_nop 0
	s_add_u32 s94, s78, 0x10000
	s_addc_u32 s95, s79, 0
	ds_read_b128 v[176:179], v136
	ds_read_b128 v[180:183], v136 offset:4096
	ds_read_b128 v[184:187], v136 offset:64
	ds_read_b128 v[188:191], v136 offset:4160
	s_waitcnt lgkmcnt(2)
	v_sub_f32_e32 v126, v126, v192
	v_mul_f32_e32 v126, v126, v193
	v_fma_f32 v126, v176, v126, v180
	v_sub_f32_e32 v127, v127, v192
	v_mul_f32_e32 v127, v127, v193
	v_fma_f32 v127, v177, v127, v181
	v_sub_f32_e32 v128, v128, v192
	v_mul_f32_e32 v128, v128, v193
	v_fma_f32 v128, v178, v128, v182
	v_sub_f32_e32 v129, v129, v192
	v_mul_f32_e32 v129, v129, v193
	v_fma_f32 v129, v179, v129, v183
	global_store_dwordx4 v137, v[126:129], s[94:95] sc1
	ds_read_b128 v[176:179], v136 offset:128
	ds_read_b128 v[180:183], v136 offset:4224
	s_waitcnt lgkmcnt(2)
	v_sub_f32_e32 v122, v122, v192
	v_mul_f32_e32 v122, v122, v193
	v_fma_f32 v122, v184, v122, v188
	v_sub_f32_e32 v123, v123, v192
	v_mul_f32_e32 v123, v123, v193
	v_fma_f32 v123, v185, v123, v189
	v_sub_f32_e32 v124, v124, v192
	v_mul_f32_e32 v124, v124, v193
	v_fma_f32 v124, v186, v124, v190
	v_sub_f32_e32 v125, v125, v192
	v_mul_f32_e32 v125, v125, v193
	v_fma_f32 v125, v187, v125, v191
	global_store_dwordx4 v137, v[122:125], s[94:95] offset:64 sc1
	ds_read_b128 v[184:187], v136 offset:192
	ds_read_b128 v[188:191], v136 offset:4288
	s_waitcnt lgkmcnt(2)
	v_sub_f32_e32 v118, v118, v192
	v_mul_f32_e32 v118, v118, v193
	v_fma_f32 v118, v176, v118, v180
	v_sub_f32_e32 v119, v119, v192
	v_mul_f32_e32 v119, v119, v193
	v_fma_f32 v119, v177, v119, v181
	v_sub_f32_e32 v120, v120, v192
	v_mul_f32_e32 v120, v120, v193
	v_fma_f32 v120, v178, v120, v182
	v_sub_f32_e32 v121, v121, v192
	v_mul_f32_e32 v121, v121, v193
	v_fma_f32 v121, v179, v121, v183
	global_store_dwordx4 v137, v[118:121], s[94:95] offset:128 sc1
	ds_read_b128 v[176:179], v136 offset:256
	ds_read_b128 v[180:183], v136 offset:4352
	s_waitcnt lgkmcnt(2)
	v_sub_f32_e32 v114, v114, v192
	v_mul_f32_e32 v114, v114, v193
	v_fma_f32 v114, v184, v114, v188
	v_sub_f32_e32 v115, v115, v192
	v_mul_f32_e32 v115, v115, v193
	v_fma_f32 v115, v185, v115, v189
	v_sub_f32_e32 v116, v116, v192
	v_mul_f32_e32 v116, v116, v193
	v_fma_f32 v116, v186, v116, v190
	v_sub_f32_e32 v117, v117, v192
	v_mul_f32_e32 v117, v117, v193
	v_fma_f32 v117, v187, v117, v191
	global_store_dwordx4 v137, v[114:117], s[94:95] offset:192 sc1
	ds_read_b128 v[184:187], v136 offset:320
	ds_read_b128 v[188:191], v136 offset:4416
	s_waitcnt lgkmcnt(2)
	v_sub_f32_e32 v110, v110, v192
	v_mul_f32_e32 v110, v110, v193
	v_fma_f32 v110, v176, v110, v180
	v_sub_f32_e32 v111, v111, v192
	v_mul_f32_e32 v111, v111, v193
	v_fma_f32 v111, v177, v111, v181
	v_sub_f32_e32 v112, v112, v192
	v_mul_f32_e32 v112, v112, v193
	v_fma_f32 v112, v178, v112, v182
	v_sub_f32_e32 v113, v113, v192
	v_mul_f32_e32 v113, v113, v193
	v_fma_f32 v113, v179, v113, v183
	global_store_dwordx4 v137, v[110:113], s[94:95] offset:256 sc1
	ds_read_b128 v[176:179], v136 offset:384
	ds_read_b128 v[180:183], v136 offset:4480
	s_waitcnt lgkmcnt(2)
	v_sub_f32_e32 v106, v106, v192
	v_mul_f32_e32 v106, v106, v193
	v_fma_f32 v106, v184, v106, v188
	v_sub_f32_e32 v107, v107, v192
	v_mul_f32_e32 v107, v107, v193
	v_fma_f32 v107, v185, v107, v189
	v_sub_f32_e32 v108, v108, v192
	v_mul_f32_e32 v108, v108, v193
	v_fma_f32 v108, v186, v108, v190
	v_sub_f32_e32 v109, v109, v192
	v_mul_f32_e32 v109, v109, v193
	v_fma_f32 v109, v187, v109, v191
	global_store_dwordx4 v137, v[106:109], s[94:95] offset:320 sc1
	ds_read_b128 v[184:187], v136 offset:448
	ds_read_b128 v[188:191], v136 offset:4544
	s_waitcnt lgkmcnt(2)
	v_sub_f32_e32 v102, v102, v192
	v_mul_f32_e32 v102, v102, v193
	v_fma_f32 v102, v176, v102, v180
	v_sub_f32_e32 v103, v103, v192
	v_mul_f32_e32 v103, v103, v193
	v_fma_f32 v103, v177, v103, v181
	v_sub_f32_e32 v104, v104, v192
	v_mul_f32_e32 v104, v104, v193
	v_fma_f32 v104, v178, v104, v182
	v_sub_f32_e32 v105, v105, v192
	v_mul_f32_e32 v105, v105, v193
	v_fma_f32 v105, v179, v105, v183
	global_store_dwordx4 v137, v[102:105], s[94:95] offset:384 sc1
	s_waitcnt lgkmcnt(0)
	v_sub_f32_e32 v66, v66, v192
	v_mul_f32_e32 v66, v66, v193
	v_fma_f32 v66, v184, v66, v188
	v_sub_f32_e32 v67, v67, v192
	v_mul_f32_e32 v67, v67, v193
	v_fma_f32 v67, v185, v67, v189
	v_sub_f32_e32 v68, v68, v192
	v_mul_f32_e32 v68, v68, v193
	v_fma_f32 v68, v186, v68, v190
	v_sub_f32_e32 v69, v69, v192
	v_mul_f32_e32 v69, v69, v193
	v_fma_f32 v69, v187, v69, v191
	global_store_dwordx4 v137, v[66:69], s[94:95] offset:448 sc1
	s_waitcnt vmcnt(20) lgkmcnt(0)
	s_barrier
; DI float bf2f(unsigned b) { return __uint_as_float(b << 16); }
; DI void unit_O(const Params& p, char* lds, int l, int tile, int glu_tiles, int tile_b) {
;     ...
;         float s2[2], ss2[2];
; #pragma unroll
;         for (int mh = 0; mh < 2; ++mh) {
;             const int mt = half * 2 + mh, rl = mh * 16 + l15;
;             float s = 0.f, ss = 0.f;
; #pragma unroll
;             for (int nt = 0; nt < 8; ++nt) {
;                 f32x4 xr;
;                 if (l == 0) {
;                     const int chunk = wid * 32 + nt * 4 + quad;
;                     xr = *(const f32x4*)(XR + rl * 4096 + ((chunk ^ l15) << 4));
;                 } else {
;                     const u32x2 hb = *(const u32x2*)(XR + ((wid * 4 + (nt >> 1)) * 32 + rl) * 64 + (nt & 1) * 32 + quad * 8);
;                     xr = (f32x4){bf2f(hb[0] & 0xffffu), bf2f(hb[0] >> 16), bf2f(hb[1] & 0xffffu), bf2f(hb[1] >> 16)};
;                 }
; #pragma unroll
;                 for (int i = 0; i < 4; ++i) { const float v = acc[mt][nt][i] + DN_ALPHA * xr[i]; acc[mt][nt][i] = v; s += v; ss += v * v; }
;             }
;             s2[mh] = s; ss2[mh] = ss;
;         }
; #pragma unroll
;         for (int mh = 0; mh < 2; ++mh) { s2[mh] += __shfl_xor(s2[mh], 16); ss2[mh] += __shfl_xor(ss2[mh], 16); }
; #pragma unroll
;         for (int mh = 0; mh < 2; ++mh) { s2[mh] += __shfl_xor(s2[mh], 32); ss2[mh] += __shfl_xor(ss2[mh], 32); }
;         if (quad == 0) {
; #pragma unroll
;             for (int mh = 0; mh < 2; ++mh) *(f32x2*)&red[((mh * 16 + l15) * 8 + wid) * 2] = (f32x2){s2[mh], ss2[mh]};
;         }
	ds_read_b64 v[180:181], v133 offset:0
	ds_read_b64 v[182:183], v133 offset:32
	ds_read_b64 v[184:185], v133 offset:1024
	ds_read_b64 v[186:187], v133 offset:1056
	ds_read_b64 v[188:189], v133 offset:2048
	ds_read_b64 v[190:191], v133 offset:2080
	ds_read_b64 v[192:193], v133 offset:3072
	ds_read_b64 v[194:195], v133 offset:3104
	s_waitcnt lgkmcnt(7)
	v_lshlrev_b32_e32 v144, 16, v180
	v_and_b32_e32 v145, 0xffff0000, v180
	v_lshlrev_b32_e32 v146, 16, v181
	v_and_b32_e32 v147, 0xffff0000, v181
	v_fmac_f32_e32 v34, s58, v144
	v_fmac_f32_e32 v35, s58, v145
	v_fmac_f32_e32 v36, s58, v146
	v_fmac_f32_e32 v37, s58, v147
	v_mov_b32_e32 v196, v34
	v_mul_f32_e32 v197, v34, v34
	v_mov_b32_e32 v130, v35
	v_mul_f32_e32 v142, v35, v35
	v_add_f32_e32 v196, v196, v36
	v_fmac_f32_e32 v197, v36, v36
	v_add_f32_e32 v130, v130, v37
	v_fmac_f32_e32 v142, v37, v37
	s_waitcnt lgkmcnt(6)
	v_lshlrev_b32_e32 v148, 16, v182
	v_and_b32_e32 v149, 0xffff0000, v182
	v_lshlrev_b32_e32 v150, 16, v183
	v_and_b32_e32 v151, 0xffff0000, v183
	v_fmac_f32_e32 v30, s58, v148
	v_fmac_f32_e32 v31, s58, v149
	v_fmac_f32_e32 v32, s58, v150
	v_fmac_f32_e32 v33, s58, v151
	v_add_f32_e32 v196, v196, v30
	v_fmac_f32_e32 v197, v30, v30
	v_add_f32_e32 v130, v130, v31
	v_fmac_f32_e32 v142, v31, v31
	v_add_f32_e32 v196, v196, v32
	v_fmac_f32_e32 v197, v32, v32
	v_add_f32_e32 v130, v130, v33
	v_fmac_f32_e32 v142, v33, v33
	s_waitcnt lgkmcnt(5)
	v_lshlrev_b32_e32 v152, 16, v184
	v_and_b32_e32 v153, 0xffff0000, v184
	v_lshlrev_b32_e32 v154, 16, v185
	v_and_b32_e32 v155, 0xffff0000, v185
	v_fmac_f32_e32 v26, s58, v152
	v_fmac_f32_e32 v27, s58, v153
	v_fmac_f32_e32 v28, s58, v154
	v_fmac_f32_e32 v29, s58, v155
	v_add_f32_e32 v196, v196, v26
	v_fmac_f32_e32 v197, v26, v26
	v_add_f32_e32 v130, v130, v27
	v_fmac_f32_e32 v142, v27, v27
	v_add_f32_e32 v196, v196, v28
	v_fmac_f32_e32 v197, v28, v28
	v_add_f32_e32 v130, v130, v29
	v_fmac_f32_e32 v142, v29, v29
	s_waitcnt lgkmcnt(4)
	v_lshlrev_b32_e32 v156, 16, v186
	v_and_b32_e32 v157, 0xffff0000, v186
	v_lshlrev_b32_e32 v158, 16, v187
	v_and_b32_e32 v159, 0xffff0000, v187
	v_fmac_f32_e32 v22, s58, v156
	v_fmac_f32_e32 v23, s58, v157
	v_fmac_f32_e32 v24, s58, v158
	v_fmac_f32_e32 v25, s58, v159
	v_add_f32_e32 v196, v196, v22
	v_fmac_f32_e32 v197, v22, v22
	v_add_f32_e32 v130, v130, v23
	v_fmac_f32_e32 v142, v23, v23
	v_add_f32_e32 v196, v196, v24
	v_fmac_f32_e32 v197, v24, v24
	v_add_f32_e32 v130, v130, v25
	v_fmac_f32_e32 v142, v25, v25
	s_waitcnt lgkmcnt(3)
	v_lshlrev_b32_e32 v160, 16, v188
	v_and_b32_e32 v161, 0xffff0000, v188
	v_lshlrev_b32_e32 v162, 16, v189
	v_and_b32_e32 v163, 0xffff0000, v189
	v_fmac_f32_e32 v18, s58, v160
	v_fmac_f32_e32 v19, s58, v161
	v_fmac_f32_e32 v20, s58, v162
	v_fmac_f32_e32 v21, s58, v163
	v_add_f32_e32 v196, v196, v18
	v_fmac_f32_e32 v197, v18, v18
	v_add_f32_e32 v130, v130, v19
	v_fmac_f32_e32 v142, v19, v19
	v_add_f32_e32 v196, v196, v20
	v_fmac_f32_e32 v197, v20, v20
	v_add_f32_e32 v130, v130, v21
	v_fmac_f32_e32 v142, v21, v21
	s_waitcnt lgkmcnt(2)
	v_lshlrev_b32_e32 v164, 16, v190
	v_and_b32_e32 v165, 0xffff0000, v190
	v_lshlrev_b32_e32 v166, 16, v191
	v_and_b32_e32 v167, 0xffff0000, v191
	v_fmac_f32_e32 v14, s58, v164
	v_fmac_f32_e32 v15, s58, v165
	v_fmac_f32_e32 v16, s58, v166
	v_fmac_f32_e32 v17, s58, v167
	v_add_f32_e32 v196, v196, v14
	v_fmac_f32_e32 v197, v14, v14
	v_add_f32_e32 v130, v130, v15
	v_fmac_f32_e32 v142, v15, v15
	v_add_f32_e32 v196, v196, v16
	v_fmac_f32_e32 v197, v16, v16
	v_add_f32_e32 v130, v130, v17
	v_fmac_f32_e32 v142, v17, v17
	s_waitcnt lgkmcnt(1)
	v_lshlrev_b32_e32 v168, 16, v192
	v_and_b32_e32 v169, 0xffff0000, v192
	v_lshlrev_b32_e32 v170, 16, v193
	v_and_b32_e32 v171, 0xffff0000, v193
	v_fmac_f32_e32 v10, s58, v168
	v_fmac_f32_e32 v11, s58, v169
	v_fmac_f32_e32 v12, s58, v170
	v_fmac_f32_e32 v13, s58, v171
	v_add_f32_e32 v196, v196, v10
	v_fmac_f32_e32 v197, v10, v10
	v_add_f32_e32 v130, v130, v11
	v_fmac_f32_e32 v142, v11, v11
	v_add_f32_e32 v196, v196, v12
	v_fmac_f32_e32 v197, v12, v12
	v_add_f32_e32 v130, v130, v13
	v_fmac_f32_e32 v142, v13, v13
	s_waitcnt lgkmcnt(0)
	v_lshlrev_b32_e32 v172, 16, v194
	v_and_b32_e32 v173, 0xffff0000, v194
	v_lshlrev_b32_e32 v174, 16, v195
	v_and_b32_e32 v175, 0xffff0000, v195
	v_fmac_f32_e32 v6, s58, v172
	v_fmac_f32_e32 v7, s58, v173
	v_fmac_f32_e32 v8, s58, v174
	v_fmac_f32_e32 v9, s58, v175
	v_add_f32_e32 v196, v196, v6
	v_fmac_f32_e32 v197, v6, v6
	v_add_f32_e32 v130, v130, v7
	v_fmac_f32_e32 v142, v7, v7
	v_add_f32_e32 v196, v196, v8
	v_fmac_f32_e32 v197, v8, v8
	v_add_f32_e32 v130, v130, v9
	v_fmac_f32_e32 v142, v9, v9
	v_add_f32_e32 v196, v196, v130
	v_add_f32_e32 v197, v197, v142
	v_mov_b32_e32 v198, v196
	v_mov_b32_e32 v199, v197
	s_nop 1
	v_permlane16_swap_b32 v198, v196
	v_permlane16_swap_b32 v199, v197
	v_add_f32_e32 v196, v196, v198
	v_add_f32_e32 v197, v197, v199
	v_mov_b32_e32 v198, v196
	v_mov_b32_e32 v199, v197
	s_nop 1
	v_permlane32_swap_b32 v198, v196
	v_permlane32_swap_b32 v199, v197
	v_add_f32_e32 v196, v196, v198
	v_add_f32_e32 v197, v197, v199
	s_mov_b64 exec, 0xffff
	ds_write_b64 v134, v[196:197]
	s_mov_b64 exec, -1
	s_waitcnt lgkmcnt(0)
	s_barrier
; DI unsigned pk2(float lo, float hi) { const f32x2 v = {lo, hi}; const bf16x2_t b = __builtin_convertvector(v, bf16x2_t); return __builtin_bit_cast(unsigned, b); }
; DI size_t xb_off(int tok, int col) { return ((size_t)(((tok >> 7) * 32 + (col >> 5)) * 128 + (tok & 127))) * 32 + (col & 31); }
; DI void unit_O(const Params& p, char* lds, int l, int tile, int glu_tiles, int tile_b) {
;     ...
;         for (int mh = 0; mh < 2; ++mh) {
;             const int mt = half * 2 + mh, rl = mh * 16 + l15, row = mt * 16 + l15;
;             float s = 0.f, ss = 0.f;
; #pragma unroll
;             for (int w = 0; w < 4; ++w) { const f32x4 v = *(const f32x4*)&red[rl * 16 + 4 * w]; s += v[0] + v[2]; ss += v[1] + v[3]; }
;             const float mu = s * (1.f / 1024.f);
;             const float var = ss * (1.f / 1024.f) - mu * mu;
;             const float rs = rsqrtf(var + LN_EPS);
;             float* orow = xo + (r0 + row) * 1024 + wid * 128 + quad * 4;
;             bf16_t* brow = xbo + xb_off((int)r0 + row, wid * 128) + quad * 4;
;             const float* gp = GB + wid * 128 + quad * 4;
; #pragma unroll
;             for (int nt = 0; nt < 8; ++nt) {
;                 const f32x4 g = *(const f32x4*)(gp + nt * 16), bb = *(const f32x4*)(gp + 1024 + nt * 16);
;                 f32x4 o;
; #pragma unroll
;                 for (int i = 0; i < 4; ++i) o[i] = (acc[mt][nt][i] - mu) * rs * g[i] + bb[i];
;                 if (l == 0) *(u32x2*)(brow + (nt >> 1) * 4096 + (nt & 1) * 16) = (u32x2){pk2(o[0], o[1]), pk2(o[2], o[3])};
;                 else *(f32x4*)(orow + nt * 16) = o;
;             }
;         }
	ds_read_b128 v[160:163], v135 offset:0
	ds_read_b128 v[164:167], v135 offset:16
	ds_read_b128 v[168:171], v135 offset:32
	ds_read_b128 v[172:175], v135 offset:48
	s_waitcnt lgkmcnt(0)
	v_add_f32_e32 v160, v160, v162
	v_add_f32_e32 v161, v161, v163
	v_add_f32_e32 v164, v164, v166
	v_add_f32_e32 v165, v165, v167
	v_add_f32_e32 v168, v168, v170
	v_add_f32_e32 v169, v169, v171
	v_add_f32_e32 v172, v172, v174
	v_add_f32_e32 v173, v173, v175
	v_add_f32_e32 v160, v160, v164
	v_add_f32_e32 v161, v161, v165
	v_add_f32_e32 v168, v168, v172
	v_add_f32_e32 v169, v169, v173
	v_add_f32_e32 v160, v160, v168
	v_add_f32_e32 v161, v161, v169
	v_mul_f32_e32 v192, 0x3a800000, v160
	v_mul_f32_e32 v193, 0x3a800000, v161
	v_fma_f32 v193, -v192, v192, v193
	v_add_f32_e32 v193, 0x3727c5ac, v193
	v_rsq_f32_e32 v193, v193
	s_nop 0
	s_add_u32 s94, s78, 0x20000
	s_addc_u32 s95, s79, 0
	ds_read_b128 v[176:179], v136
	ds_read_b128 v[180:183], v136 offset:4096
	ds_read_b128 v[184:187], v136 offset:64
	ds_read_b128 v[188:191], v136 offset:4160
	s_waitcnt lgkmcnt(2)
	v_sub_f32_e32 v34, v34, v192
	v_mul_f32_e32 v34, v34, v193
	v_fma_f32 v34, v176, v34, v180
	v_sub_f32_e32 v35, v35, v192
	v_mul_f32_e32 v35, v35, v193
	v_fma_f32 v35, v177, v35, v181
	v_sub_f32_e32 v36, v36, v192
	v_mul_f32_e32 v36, v36, v193
	v_fma_f32 v36, v178, v36, v182
	v_sub_f32_e32 v37, v37, v192
	v_mul_f32_e32 v37, v37, v193
	v_fma_f32 v37, v179, v37, v183
	global_store_dwordx4 v137, v[34:37], s[94:95] sc1
	ds_read_b128 v[176:179], v136 offset:128
	ds_read_b128 v[180:183], v136 offset:4224
	s_waitcnt lgkmcnt(2)
	v_sub_f32_e32 v30, v30, v192
	v_mul_f32_e32 v30, v30, v193
	v_fma_f32 v30, v184, v30, v188
	v_sub_f32_e32 v31, v31, v192
	v_mul_f32_e32 v31, v31, v193
	v_fma_f32 v31, v185, v31, v189
	v_sub_f32_e32 v32, v32, v192
	v_mul_f32_e32 v32, v32, v193
	v_fma_f32 v32, v186, v32, v190
	v_sub_f32_e32 v33, v33, v192
	v_mul_f32_e32 v33, v33, v193
	v_fma_f32 v33, v187, v33, v191
	global_store_dwordx4 v137, v[30:33], s[94:95] offset:64 sc1
	ds_read_b128 v[184:187], v136 offset:192
	ds_read_b128 v[188:191], v136 offset:4288
	s_waitcnt lgkmcnt(2)
	v_sub_f32_e32 v26, v26, v192
	v_mul_f32_e32 v26, v26, v193
	v_fma_f32 v26, v176, v26, v180
	v_sub_f32_e32 v27, v27, v192
	v_mul_f32_e32 v27, v27, v193
	v_fma_f32 v27, v177, v27, v181
	v_sub_f32_e32 v28, v28, v192
	v_mul_f32_e32 v28, v28, v193
	v_fma_f32 v28, v178, v28, v182
	v_sub_f32_e32 v29, v29, v192
	v_mul_f32_e32 v29, v29, v193
	v_fma_f32 v29, v179, v29, v183
	global_store_dwordx4 v137, v[26:29], s[94:95] offset:128 sc1
	ds_read_b128 v[176:179], v136 offset:256
	ds_read_b128 v[180:183], v136 offset:4352
	s_waitcnt lgkmcnt(2)
	v_sub_f32_e32 v22, v22, v192
	v_mul_f32_e32 v22, v22, v193
	v_fma_f32 v22, v184, v22, v188
	v_sub_f32_e32 v23, v23, v192
	v_mul_f32_e32 v23, v23, v193
	v_fma_f32 v23, v185, v23, v189
	v_sub_f32_e32 v24, v24, v192
	v_mul_f32_e32 v24, v24, v193
	v_fma_f32 v24, v186, v24, v190
	v_sub_f32_e32 v25, v25, v192
	v_mul_f32_e32 v25, v25, v193
	v_fma_f32 v25, v187, v25, v191
	global_store_dwordx4 v137, v[22:25], s[94:95] offset:192 sc1
	ds_read_b128 v[184:187], v136 offset:320
	ds_read_b128 v[188:191], v136 offset:4416
	s_waitcnt lgkmcnt(2)
	v_sub_f32_e32 v18, v18, v192
	v_mul_f32_e32 v18, v18, v193
	v_fma_f32 v18, v176, v18, v180
	v_sub_f32_e32 v19, v19, v192
	v_mul_f32_e32 v19, v19, v193
	v_fma_f32 v19, v177, v19, v181
	v_sub_f32_e32 v20, v20, v192
	v_mul_f32_e32 v20, v20, v193
	v_fma_f32 v20, v178, v20, v182
	v_sub_f32_e32 v21, v21, v192
	v_mul_f32_e32 v21, v21, v193
	v_fma_f32 v21, v179, v21, v183
	global_store_dwordx4 v137, v[18:21], s[94:95] offset:256 sc1
	ds_read_b128 v[176:179], v136 offset:384
	ds_read_b128 v[180:183], v136 offset:4480
	s_waitcnt lgkmcnt(2)
	v_sub_f32_e32 v14, v14, v192
	v_mul_f32_e32 v14, v14, v193
	v_fma_f32 v14, v184, v14, v188
	v_sub_f32_e32 v15, v15, v192
	v_mul_f32_e32 v15, v15, v193
	v_fma_f32 v15, v185, v15, v189
	v_sub_f32_e32 v16, v16, v192
	v_mul_f32_e32 v16, v16, v193
	v_fma_f32 v16, v186, v16, v190
	v_sub_f32_e32 v17, v17, v192
	v_mul_f32_e32 v17, v17, v193
	v_fma_f32 v17, v187, v17, v191
	global_store_dwordx4 v137, v[14:17], s[94:95] offset:320 sc1
	ds_read_b128 v[184:187], v136 offset:448
	ds_read_b128 v[188:191], v136 offset:4544
	s_waitcnt lgkmcnt(2)
	v_sub_f32_e32 v10, v10, v192
	v_mul_f32_e32 v10, v10, v193
	v_fma_f32 v10, v176, v10, v180
	v_sub_f32_e32 v11, v11, v192
	v_mul_f32_e32 v11, v11, v193
	v_fma_f32 v11, v177, v11, v181
	v_sub_f32_e32 v12, v12, v192
	v_mul_f32_e32 v12, v12, v193
	v_fma_f32 v12, v178, v12, v182
	v_sub_f32_e32 v13, v13, v192
	v_mul_f32_e32 v13, v13, v193
	v_fma_f32 v13, v179, v13, v183
	global_store_dwordx4 v137, v[10:13], s[94:95] offset:384 sc1
	s_waitcnt lgkmcnt(0)
	v_sub_f32_e32 v6, v6, v192
	v_mul_f32_e32 v6, v6, v193
	v_fma_f32 v6, v184, v6, v188
	v_sub_f32_e32 v7, v7, v192
	v_mul_f32_e32 v7, v7, v193
	v_fma_f32 v7, v185, v7, v189
	v_sub_f32_e32 v8, v8, v192
	v_mul_f32_e32 v8, v8, v193
	v_fma_f32 v8, v186, v8, v190
	v_sub_f32_e32 v9, v9, v192
	v_mul_f32_e32 v9, v9, v193
	v_fma_f32 v9, v187, v9, v191
	global_store_dwordx4 v137, v[6:9], s[94:95] offset:448 sc1
	s_waitcnt vmcnt(16) lgkmcnt(0)
	s_barrier
; DI float bf2f(unsigned b) { return __uint_as_float(b << 16); }
; DI void unit_O(const Params& p, char* lds, int l, int tile, int glu_tiles, int tile_b) {
;     ...
;         float s2[2], ss2[2];
; #pragma unroll
;         for (int mh = 0; mh < 2; ++mh) {
;             const int mt = half * 2 + mh, rl = mh * 16 + l15;
;             float s = 0.f, ss = 0.f;
; #pragma unroll
;             for (int nt = 0; nt < 8; ++nt) {
;                 f32x4 xr;
;                 if (l == 0) {
;                     const int chunk = wid * 32 + nt * 4 + quad;
;                     xr = *(const f32x4*)(XR + rl * 4096 + ((chunk ^ l15) << 4));
;                 } else {
;                     const u32x2 hb = *(const u32x2*)(XR + ((wid * 4 + (nt >> 1)) * 32 + rl) * 64 + (nt & 1) * 32 + quad * 8);
;                     xr = (f32x4){bf2f(hb[0] & 0xffffu), bf2f(hb[0] >> 16), bf2f(hb[1] & 0xffffu), bf2f(hb[1] >> 16)};
;                 }
; #pragma unroll
;                 for (int i = 0; i < 4; ++i) { const float v = acc[mt][nt][i] + DN_ALPHA * xr[i]; acc[mt][nt][i] = v; s += v; ss += v * v; }
;             }
;             s2[mh] = s; ss2[mh] = ss;
;         }
; #pragma unroll
;         for (int mh = 0; mh < 2; ++mh) { s2[mh] += __shfl_xor(s2[mh], 16); ss2[mh] += __shfl_xor(ss2[mh], 16); }
; #pragma unroll
;         for (int mh = 0; mh < 2; ++mh) { s2[mh] += __shfl_xor(s2[mh], 32); ss2[mh] += __shfl_xor(ss2[mh], 32); }
;         if (quad == 0) {
; #pragma unroll
;             for (int mh = 0; mh < 2; ++mh) *(f32x2*)&red[((mh * 16 + l15) * 8 + wid) * 2] = (f32x2){s2[mh], ss2[mh]};
;         }
	ds_read_b64 v[180:181], v133 offset:32768
	ds_read_b64 v[182:183], v133 offset:32800
	ds_read_b64 v[184:185], v133 offset:33792
	ds_read_b64 v[186:187], v133 offset:33824
	ds_read_b64 v[188:189], v133 offset:34816
	ds_read_b64 v[190:191], v133 offset:34848
	ds_read_b64 v[192:193], v133 offset:35840
	ds_read_b64 v[194:195], v133 offset:35872
	s_waitcnt lgkmcnt(7)
	v_lshlrev_b32_e32 v144, 16, v180
	v_and_b32_e32 v145, 0xffff0000, v180
	v_lshlrev_b32_e32 v146, 16, v181
	v_and_b32_e32 v147, 0xffff0000, v181
	v_fmac_f32_e32 v62, s58, v144
	v_fmac_f32_e32 v63, s58, v145
	v_fmac_f32_e32 v64, s58, v146
	v_fmac_f32_e32 v65, s58, v147
	v_mov_b32_e32 v196, v62
	v_mul_f32_e32 v197, v62, v62
	v_mov_b32_e32 v130, v63
	v_mul_f32_e32 v142, v63, v63
	v_add_f32_e32 v196, v196, v64
	v_fmac_f32_e32 v197, v64, v64
	v_add_f32_e32 v130, v130, v65
	v_fmac_f32_e32 v142, v65, v65
	s_waitcnt lgkmcnt(6)
	v_lshlrev_b32_e32 v148, 16, v182
	v_and_b32_e32 v149, 0xffff0000, v182
	v_lshlrev_b32_e32 v150, 16, v183
	v_and_b32_e32 v151, 0xffff0000, v183
	v_fmac_f32_e32 v58, s58, v148
	v_fmac_f32_e32 v59, s58, v149
	v_fmac_f32_e32 v60, s58, v150
	v_fmac_f32_e32 v61, s58, v151
	v_add_f32_e32 v196, v196, v58
	v_fmac_f32_e32 v197, v58, v58
	v_add_f32_e32 v130, v130, v59
	v_fmac_f32_e32 v142, v59, v59
	v_add_f32_e32 v196, v196, v60
	v_fmac_f32_e32 v197, v60, v60
	v_add_f32_e32 v130, v130, v61
	v_fmac_f32_e32 v142, v61, v61
	s_waitcnt lgkmcnt(5)
	v_lshlrev_b32_e32 v152, 16, v184
	v_and_b32_e32 v153, 0xffff0000, v184
	v_lshlrev_b32_e32 v154, 16, v185
	v_and_b32_e32 v155, 0xffff0000, v185
	v_fmac_f32_e32 v54, s58, v152
	v_fmac_f32_e32 v55, s58, v153
	v_fmac_f32_e32 v56, s58, v154
	v_fmac_f32_e32 v57, s58, v155
	v_add_f32_e32 v196, v196, v54
	v_fmac_f32_e32 v197, v54, v54
	v_add_f32_e32 v130, v130, v55
	v_fmac_f32_e32 v142, v55, v55
	v_add_f32_e32 v196, v196, v56
	v_fmac_f32_e32 v197, v56, v56
	v_add_f32_e32 v130, v130, v57
	v_fmac_f32_e32 v142, v57, v57
	s_waitcnt lgkmcnt(4)
	v_lshlrev_b32_e32 v156, 16, v186
	v_and_b32_e32 v157, 0xffff0000, v186
	v_lshlrev_b32_e32 v158, 16, v187
	v_and_b32_e32 v159, 0xffff0000, v187
	v_fmac_f32_e32 v50, s58, v156
	v_fmac_f32_e32 v51, s58, v157
	v_fmac_f32_e32 v52, s58, v158
	v_fmac_f32_e32 v53, s58, v159
	v_add_f32_e32 v196, v196, v50
	v_fmac_f32_e32 v197, v50, v50
	v_add_f32_e32 v130, v130, v51
	v_fmac_f32_e32 v142, v51, v51
	v_add_f32_e32 v196, v196, v52
	v_fmac_f32_e32 v197, v52, v52
	v_add_f32_e32 v130, v130, v53
	v_fmac_f32_e32 v142, v53, v53
	s_waitcnt lgkmcnt(3)
	v_lshlrev_b32_e32 v160, 16, v188
	v_and_b32_e32 v161, 0xffff0000, v188
	v_lshlrev_b32_e32 v162, 16, v189
	v_and_b32_e32 v163, 0xffff0000, v189
	v_fmac_f32_e32 v46, s58, v160
	v_fmac_f32_e32 v47, s58, v161
	v_fmac_f32_e32 v48, s58, v162
	v_fmac_f32_e32 v49, s58, v163
	v_add_f32_e32 v196, v196, v46
	v_fmac_f32_e32 v197, v46, v46
	v_add_f32_e32 v130, v130, v47
	v_fmac_f32_e32 v142, v47, v47
	v_add_f32_e32 v196, v196, v48
	v_fmac_f32_e32 v197, v48, v48
	v_add_f32_e32 v130, v130, v49
	v_fmac_f32_e32 v142, v49, v49
	s_waitcnt lgkmcnt(2)
	v_lshlrev_b32_e32 v164, 16, v190
	v_and_b32_e32 v165, 0xffff0000, v190
	v_lshlrev_b32_e32 v166, 16, v191
	v_and_b32_e32 v167, 0xffff0000, v191
	v_fmac_f32_e32 v42, s58, v164
	v_fmac_f32_e32 v43, s58, v165
	v_fmac_f32_e32 v44, s58, v166
	v_fmac_f32_e32 v45, s58, v167
	v_add_f32_e32 v196, v196, v42
	v_fmac_f32_e32 v197, v42, v42
	v_add_f32_e32 v130, v130, v43
	v_fmac_f32_e32 v142, v43, v43
	v_add_f32_e32 v196, v196, v44
	v_fmac_f32_e32 v197, v44, v44
	v_add_f32_e32 v130, v130, v45
	v_fmac_f32_e32 v142, v45, v45
	s_waitcnt lgkmcnt(1)
	v_lshlrev_b32_e32 v168, 16, v192
	v_and_b32_e32 v169, 0xffff0000, v192
	v_lshlrev_b32_e32 v170, 16, v193
	v_and_b32_e32 v171, 0xffff0000, v193
	v_fmac_f32_e32 v38, s58, v168
	v_fmac_f32_e32 v39, s58, v169
	v_fmac_f32_e32 v40, s58, v170
	v_fmac_f32_e32 v41, s58, v171
	v_add_f32_e32 v196, v196, v38
	v_fmac_f32_e32 v197, v38, v38
	v_add_f32_e32 v130, v130, v39
	v_fmac_f32_e32 v142, v39, v39
	v_add_f32_e32 v196, v196, v40
	v_fmac_f32_e32 v197, v40, v40
	v_add_f32_e32 v130, v130, v41
	v_fmac_f32_e32 v142, v41, v41
	s_waitcnt lgkmcnt(0)
	v_lshlrev_b32_e32 v172, 16, v194
	v_and_b32_e32 v173, 0xffff0000, v194
	v_lshlrev_b32_e32 v174, 16, v195
	v_and_b32_e32 v175, 0xffff0000, v195
	v_fmac_f32_e32 v2, s58, v172
	v_fmac_f32_e32 v3, s58, v173
	v_fmac_f32_e32 v4, s58, v174
	v_fmac_f32_e32 v5, s58, v175
	v_add_f32_e32 v196, v196, v2
	v_fmac_f32_e32 v197, v2, v2
	v_add_f32_e32 v130, v130, v3
	v_fmac_f32_e32 v142, v3, v3
	v_add_f32_e32 v196, v196, v4
	v_fmac_f32_e32 v197, v4, v4
	v_add_f32_e32 v130, v130, v5
	v_fmac_f32_e32 v142, v5, v5
	v_add_f32_e32 v196, v196, v130
	v_add_f32_e32 v197, v197, v142
	v_mov_b32_e32 v198, v196
	v_mov_b32_e32 v199, v197
	s_nop 1
	v_permlane16_swap_b32 v198, v196
	v_permlane16_swap_b32 v199, v197
	v_add_f32_e32 v196, v196, v198
	v_add_f32_e32 v197, v197, v199
	v_mov_b32_e32 v198, v196
	v_mov_b32_e32 v199, v197
	s_nop 1
	v_permlane32_swap_b32 v198, v196
	v_permlane32_swap_b32 v199, v197
	v_add_f32_e32 v196, v196, v198
	v_add_f32_e32 v197, v197, v199
	s_mov_b64 exec, 0xffff
	ds_write_b64 v134, v[196:197]
	s_mov_b64 exec, -1
	s_waitcnt lgkmcnt(0)
	s_barrier
; DI unsigned pk2(float lo, float hi) { const f32x2 v = {lo, hi}; const bf16x2_t b = __builtin_convertvector(v, bf16x2_t); return __builtin_bit_cast(unsigned, b); }
; DI size_t xb_off(int tok, int col) { return ((size_t)(((tok >> 7) * 32 + (col >> 5)) * 128 + (tok & 127))) * 32 + (col & 31); }
; DI void unit_O(const Params& p, char* lds, int l, int tile, int glu_tiles, int tile_b) {
;     ...
;         for (int mh = 0; mh < 2; ++mh) {
;             const int mt = half * 2 + mh, rl = mh * 16 + l15, row = mt * 16 + l15;
;             float s = 0.f, ss = 0.f;
; #pragma unroll
;             for (int w = 0; w < 4; ++w) { const f32x4 v = *(const f32x4*)&red[rl * 16 + 4 * w]; s += v[0] + v[2]; ss += v[1] + v[3]; }
;             const float mu = s * (1.f / 1024.f);
;             const float var = ss * (1.f / 1024.f) - mu * mu;
;             const float rs = rsqrtf(var + LN_EPS);
;             float* orow = xo + (r0 + row) * 1024 + wid * 128 + quad * 4;
;             bf16_t* brow = xbo + xb_off((int)r0 + row, wid * 128) + quad * 4;
;             const float* gp = GB + wid * 128 + quad * 4;
; #pragma unroll
;             for (int nt = 0; nt < 8; ++nt) {
;                 const f32x4 g = *(const f32x4*)(gp + nt * 16), bb = *(const f32x4*)(gp + 1024 + nt * 16);
;                 f32x4 o;
; #pragma unroll
;                 for (int i = 0; i < 4; ++i) o[i] = (acc[mt][nt][i] - mu) * rs * g[i] + bb[i];
;                 if (l == 0) *(u32x2*)(brow + (nt >> 1) * 4096 + (nt & 1) * 16) = (u32x2){pk2(o[0], o[1]), pk2(o[2], o[3])};
;                 else *(f32x4*)(orow + nt * 16) = o;
;             }
;         }
	ds_read_b128 v[160:163], v135 offset:0
	ds_read_b128 v[164:167], v135 offset:16
	ds_read_b128 v[168:171], v135 offset:32
	ds_read_b128 v[172:175], v135 offset:48
	s_waitcnt lgkmcnt(0)
	v_add_f32_e32 v160, v160, v162
	v_add_f32_e32 v161, v161, v163
	v_add_f32_e32 v164, v164, v166
	v_add_f32_e32 v165, v165, v167
	v_add_f32_e32 v168, v168, v170
	v_add_f32_e32 v169, v169, v171
	v_add_f32_e32 v172, v172, v174
	v_add_f32_e32 v173, v173, v175
	v_add_f32_e32 v160, v160, v164
	v_add_f32_e32 v161, v161, v165
	v_add_f32_e32 v168, v168, v172
	v_add_f32_e32 v169, v169, v173
	v_add_f32_e32 v160, v160, v168
	v_add_f32_e32 v161, v161, v169
	v_mul_f32_e32 v192, 0x3a800000, v160
	v_mul_f32_e32 v193, 0x3a800000, v161
	v_fma_f32 v193, -v192, v192, v193
	v_add_f32_e32 v193, 0x3727c5ac, v193
	v_rsq_f32_e32 v193, v193
	s_nop 0
	s_add_u32 s94, s78, 0x30000
	s_addc_u32 s95, s79, 0
	ds_read_b128 v[176:179], v136
	ds_read_b128 v[180:183], v136 offset:4096
	ds_read_b128 v[184:187], v136 offset:64
	ds_read_b128 v[188:191], v136 offset:4160
	s_waitcnt lgkmcnt(2)
	v_sub_f32_e32 v62, v62, v192
	v_mul_f32_e32 v62, v62, v193
	v_fma_f32 v62, v176, v62, v180
	v_sub_f32_e32 v63, v63, v192
	v_mul_f32_e32 v63, v63, v193
	v_fma_f32 v63, v177, v63, v181
	v_sub_f32_e32 v64, v64, v192
	v_mul_f32_e32 v64, v64, v193
	v_fma_f32 v64, v178, v64, v182
	v_sub_f32_e32 v65, v65, v192
	v_mul_f32_e32 v65, v65, v193
	v_fma_f32 v65, v179, v65, v183
	global_store_dwordx4 v137, v[62:65], s[94:95] sc1
	ds_read_b128 v[176:179], v136 offset:128
	ds_read_b128 v[180:183], v136 offset:4224
	s_waitcnt lgkmcnt(2)
	v_sub_f32_e32 v58, v58, v192
	v_mul_f32_e32 v58, v58, v193
	v_fma_f32 v58, v184, v58, v188
	v_sub_f32_e32 v59, v59, v192
	v_mul_f32_e32 v59, v59, v193
	v_fma_f32 v59, v185, v59, v189
	v_sub_f32_e32 v60, v60, v192
	v_mul_f32_e32 v60, v60, v193
	v_fma_f32 v60, v186, v60, v190
	v_sub_f32_e32 v61, v61, v192
	v_mul_f32_e32 v61, v61, v193
	v_fma_f32 v61, v187, v61, v191
	global_store_dwordx4 v137, v[58:61], s[94:95] offset:64 sc1
	ds_read_b128 v[184:187], v136 offset:192
	ds_read_b128 v[188:191], v136 offset:4288
	s_waitcnt lgkmcnt(2)
	v_sub_f32_e32 v54, v54, v192
	v_mul_f32_e32 v54, v54, v193
	v_fma_f32 v54, v176, v54, v180
	v_sub_f32_e32 v55, v55, v192
	v_mul_f32_e32 v55, v55, v193
	v_fma_f32 v55, v177, v55, v181
	v_sub_f32_e32 v56, v56, v192
	v_mul_f32_e32 v56, v56, v193
	v_fma_f32 v56, v178, v56, v182
	v_sub_f32_e32 v57, v57, v192
	v_mul_f32_e32 v57, v57, v193
	v_fma_f32 v57, v179, v57, v183
	global_store_dwordx4 v137, v[54:57], s[94:95] offset:128 sc1
	ds_read_b128 v[176:179], v136 offset:256
	ds_read_b128 v[180:183], v136 offset:4352
	s_waitcnt lgkmcnt(2)
	v_sub_f32_e32 v50, v50, v192
	v_mul_f32_e32 v50, v50, v193
	v_fma_f32 v50, v184, v50, v188
	v_sub_f32_e32 v51, v51, v192
	v_mul_f32_e32 v51, v51, v193
	v_fma_f32 v51, v185, v51, v189
	v_sub_f32_e32 v52, v52, v192
	v_mul_f32_e32 v52, v52, v193
	v_fma_f32 v52, v186, v52, v190
	v_sub_f32_e32 v53, v53, v192
	v_mul_f32_e32 v53, v53, v193
	v_fma_f32 v53, v187, v53, v191
	global_store_dwordx4 v137, v[50:53], s[94:95] offset:192 sc1
	ds_read_b128 v[184:187], v136 offset:320
	ds_read_b128 v[188:191], v136 offset:4416
	s_waitcnt lgkmcnt(2)
	v_sub_f32_e32 v46, v46, v192
	v_mul_f32_e32 v46, v46, v193
	v_fma_f32 v46, v176, v46, v180
	v_sub_f32_e32 v47, v47, v192
	v_mul_f32_e32 v47, v47, v193
	v_fma_f32 v47, v177, v47, v181
	v_sub_f32_e32 v48, v48, v192
	v_mul_f32_e32 v48, v48, v193
	v_fma_f32 v48, v178, v48, v182
	v_sub_f32_e32 v49, v49, v192
	v_mul_f32_e32 v49, v49, v193
	v_fma_f32 v49, v179, v49, v183
	global_store_dwordx4 v137, v[46:49], s[94:95] offset:256 sc1
	ds_read_b128 v[176:179], v136 offset:384
	ds_read_b128 v[180:183], v136 offset:4480
	s_waitcnt lgkmcnt(2)
	v_sub_f32_e32 v42, v42, v192
	v_mul_f32_e32 v42, v42, v193
	v_fma_f32 v42, v184, v42, v188
	v_sub_f32_e32 v43, v43, v192
	v_mul_f32_e32 v43, v43, v193
	v_fma_f32 v43, v185, v43, v189
	v_sub_f32_e32 v44, v44, v192
	v_mul_f32_e32 v44, v44, v193
	v_fma_f32 v44, v186, v44, v190
	v_sub_f32_e32 v45, v45, v192
	v_mul_f32_e32 v45, v45, v193
	v_fma_f32 v45, v187, v45, v191
	global_store_dwordx4 v137, v[42:45], s[94:95] offset:320 sc1
	ds_read_b128 v[184:187], v136 offset:448
	ds_read_b128 v[188:191], v136 offset:4544
	s_waitcnt lgkmcnt(2)
	v_sub_f32_e32 v38, v38, v192
	v_mul_f32_e32 v38, v38, v193
	v_fma_f32 v38, v176, v38, v180
	v_sub_f32_e32 v39, v39, v192
	v_mul_f32_e32 v39, v39, v193
	v_fma_f32 v39, v177, v39, v181
	v_sub_f32_e32 v40, v40, v192
	v_mul_f32_e32 v40, v40, v193
	v_fma_f32 v40, v178, v40, v182
	v_sub_f32_e32 v41, v41, v192
	v_mul_f32_e32 v41, v41, v193
	v_fma_f32 v41, v179, v41, v183
	global_store_dwordx4 v137, v[38:41], s[94:95] offset:384 sc1
	s_waitcnt lgkmcnt(0)
	v_sub_f32_e32 v2, v2, v192
	v_mul_f32_e32 v2, v2, v193
	v_fma_f32 v2, v184, v2, v188
	v_sub_f32_e32 v3, v3, v192
	v_mul_f32_e32 v3, v3, v193
	v_fma_f32 v3, v185, v3, v189
	v_sub_f32_e32 v4, v4, v192
	v_mul_f32_e32 v4, v4, v193
	v_fma_f32 v4, v186, v4, v190
	v_sub_f32_e32 v5, v5, v192
	v_mul_f32_e32 v5, v5, v193
	v_fma_f32 v5, v187, v5, v191
	global_store_dwordx4 v137, v[2:5], s[94:95] offset:448 sc1
